# latent scan step: MFMA operand fragments prefetched from LDS 5 deep; latent attention: K fragments prefetched, dead register-set copies removed, K/V staging loads cover 64 contiguous bytes per 4 lanes
# speedup vs baseline: 1.0010x; 1.0010x over previous
.LBB0_97:
	s_andn2_b64 vcc, exec, s[0:1]
	s_cbranch_vccnz .LBB0_108
	v_readlane_b32 s0, v245, 0
	s_add_i32 s40, s0, s97
	v_mov_b32_e32 v1, v149
	s_lshl_b32 s0, s40, 4
	v_ashrrev_i32_e32 v2, 1, v1
	s_and_b32 s1, s0, 0x1ff00
	s_and_b32 s0, s0, 0x80
	v_and_b32_e32 v2, 0xffffffe0, v2
	v_and_b32_e32 v8, 31, v1
	v_add_u32_e32 v2, s0, v2
	s_add_i32 s12, s1, 0xffff8000
	v_or_b32_e32 v2, v2, v8
	s_and_b32 s13, s97, 7
	v_add_u32_e32 v4, s12, v2
	v_mov_b64_e32 v[2:3], s[34:35]
	v_bfe_u32 v9, v1, 5, 1
	v_mad_i64_i32 v[4:5], s[0:1], v4, s9, v[2:3]
	s_lshl_b32 s2, s13, 7
	v_lshl_add_u64 v[112:113], v[4:5], 0, s[2:3]
	v_lshlrev_b32_e32 v4, 4, v9
	v_mov_b32_e32 v5, v0
	v_lshl_add_u64 v[6:7], v[112:113], 0, v[4:5]
	global_load_dwordx4 v[80:83], v[6:7], off
	global_load_dwordx4 v[84:87], v[6:7], off offset:32
	global_load_dwordx4 v[88:91], v[6:7], off offset:64
	global_load_dwordx4 v[92:95], v[6:7], off offset:96
	v_and_b32_e32 v5, 63, v1
	v_readlane_b32 s0, v246, 34
	s_or_b32 s0, s13, s0
	v_cmp_gt_u32_e32 vcc, 32, v5
	v_ashrrev_i32_e32 v5, 2, v1
	s_ashr_i32 s1, s0, 31
	v_add_u32_e32 v6, s12, v5
	s_lshl_b32 s2, s40, 5
	v_readlane_b32 s60, v246, 5
	v_mad_i64_i32 v[2:3], s[12:13], v6, s9, v[2:3]
	s_and_b32 s2, s2, 0x80
	v_lshlrev_b32_e32 v6, 4, v1
	s_lshl_b64 s[0:1], s[0:1], 2
	v_readlane_b32 s66, v246, 11
	v_lshl_add_u64 v[2:3], v[2:3], 0, s[2:3]
	v_and_b32_e32 v6, 0x30, v6
	v_mov_b32_e32 v7, v0
	v_readlane_b32 s67, v246, 12
	s_add_u32 s0, s66, s0
	v_readlane_b32 s2, v245, 2
	v_lshl_add_u64 v[114:115], v[2:3], 0, v[6:7]
	v_mul_lo_u32 v2, v5, s39
	s_addc_u32 s1, s67, s1
	s_add_i32 s2, s2, s97
	v_add3_u32 v122, 0, v2, v6
	v_lshlrev_b32_e32 v120, 2, v9
	v_lshrrev_b32_e32 v2, 2, v1
	s_lshl_b32 s12, s2, 4
	v_add_u32_e32 v6, 0, v4
	v_and_or_b32 v2, v2, 3, v120
	v_and_b32_e32 v3, 16, v1
	v_lshlrev_b32_e32 v4, 3, v1
	s_and_b32 s12, s12, 0x1ff00
	s_lshl_b32 s2, s2, 5
	v_lshlrev_b32_e32 v3, 1, v3
	v_and_b32_e32 v4, 24, v4
	v_mul_u32_u24_e32 v9, 0x90, v2
	v_add_u32_e32 v2, s12, v5
	s_and_b32 s2, s2, 0x80
	v_add3_u32 v7, 0, v3, v4
	v_add_u32_e32 v4, 0xffff8040, v2
	v_mov_b32_e32 v2, s2
	v_mov_b32_e32 v3, v0
	v_mad_i64_i32 v[2:3], s[12:13], v4, s9, v[2:3]
	v_and_b32_e32 v1, 3, v1
	v_lshlrev_b32_e32 v4, 4, v1
	v_mov_b32_e32 v5, v0
	v_readlane_b32 s12, v247, 43
	v_mul_u32_u24_e32 v8, 0x90, v8
	v_lshl_add_u64 v[2:3], v[2:3], 0, v[4:5]
	v_readlane_b32 s13, v247, 44
	v_cndmask_b32_e64 v121, 0, 1.0, vcc
	s_mov_b32 s2, 0
	v_lshl_add_u64 v[116:117], s[12:13], 0, v[2:3]
	v_add_u32_e32 v123, v6, v8
	v_add_u32_e32 v124, v7, v9
	v_readlane_b32 s61, v246, 6
	v_readlane_b32 s62, v246, 7
	v_readlane_b32 s63, v246, 8
	v_readlane_b32 s64, v246, 9
	v_readlane_b32 s65, v246, 10
	v_readlane_b32 s68, v246, 13
	v_readlane_b32 s69, v246, 14
	v_readlane_b32 s70, v246, 15
	v_readlane_b32 s71, v246, 16
	v_readlane_b32 s72, v246, 17
	v_readlane_b32 s73, v246, 18
	v_readlane_b32 s74, v246, 19
	v_readlane_b32 s75, v246, 20
	s_branch .LBB0_100

.LBB0_100:
	global_load_dword v1, v0, s[0:1]
	global_load_dwordx4 v[96:99], v[114:115], off offset:1024
	global_load_dwordx4 v[100:103], v[114:115], off offset:1088
	global_load_dwordx4 v[104:107], v[114:115], off offset:1280
	global_load_dwordx4 v[108:111], v[114:115], off offset:1344
	v_mov_b32_e32 v14, v0
	v_mov_b32_e32 v15, v0
	v_mov_b32_e32 v2, v0
	v_mov_b32_e32 v3, v0
	v_mov_b32_e32 v4, v0
	v_mov_b32_e32 v5, v0
	v_mov_b32_e32 v6, v0
	v_mov_b32_e32 v7, v0
	v_mov_b32_e32 v8, v0
	v_mov_b32_e32 v9, v0
	v_mov_b32_e32 v10, v0
	v_mov_b32_e32 v11, v0
	v_mov_b32_e32 v12, v0
	v_mov_b32_e32 v13, v0
	v_mov_b64_e32 v[118:119], v[116:117]
	s_mov_b32 s12, 0
	s_waitcnt vmcnt(4)
	v_mul_f32_e32 v125, 0x3fb8aa3b, v1
	v_mov_b32_e32 v1, v0
	v_mov_b64_e32 v[30:31], v[14:15]
	v_mov_b64_e32 v[46:47], v[14:15]
	v_mov_b64_e32 v[28:29], v[12:13]
	v_mov_b64_e32 v[26:27], v[10:11]
	v_mov_b64_e32 v[24:25], v[8:9]
	v_mov_b64_e32 v[22:23], v[6:7]
	v_mov_b64_e32 v[20:21], v[4:5]
	v_mov_b64_e32 v[18:19], v[2:3]
	v_mov_b64_e32 v[16:17], v[0:1]
	v_mov_b64_e32 v[44:45], v[12:13]
	v_mov_b64_e32 v[42:43], v[10:11]
	v_mov_b64_e32 v[40:41], v[8:9]
	v_mov_b64_e32 v[38:39], v[6:7]
	v_mov_b64_e32 v[36:37], v[4:5]
	v_mov_b64_e32 v[34:35], v[2:3]
	v_mov_b64_e32 v[32:33], v[0:1]
	v_mov_b32_e32 v1, v121
.LBB0_101:
	s_waitcnt lgkmcnt(0)
	s_barrier
	s_waitcnt vmcnt(3)
	ds_write_b128 v122, v[96:99]
	s_waitcnt vmcnt(2)
	ds_write_b128 v122, v[100:103] offset:64
	s_waitcnt vmcnt(1)
	ds_write_b128 v122, v[104:107] offset:9216
	s_waitcnt vmcnt(0)
	ds_write_b128 v122, v[108:111] offset:9280
	s_waitcnt lgkmcnt(0)
	s_barrier
	s_cmp_gt_u32 s12, 2
	s_cselect_b64 s[40:41], -1, 0
	s_and_b64 vcc, exec, s[40:41]
	s_cbranch_vccnz .LBB0_103
	global_load_dwordx4 v[96:99], v[118:119], off offset:-256
	global_load_dwordx4 v[100:103], v[118:119], off offset:-192
	global_load_dwordx4 v[104:107], v[118:119], off
	global_load_dwordx4 v[108:111], v[118:119], off offset:64

.LBB0_109:
	s_andn2_b64 vcc, exec, s[0:1]
	s_cbranch_vccnz .LBB0_144
	v_readlane_b32 s0, v245, 1
	v_mov_b32_e32 v1, v149
	s_add_i32 s40, s0, s97
	s_lshr_b32 s12, s40, 8
	v_ashrrev_i32_e32 v2, 1, v1
	s_bfe_u32 s13, s40, 0x50003
	v_and_b32_e32 v12, 0xffffffe0, v2
	v_and_b32_e32 v10, 31, v1
	s_lshl_b32 s0, s12, 12
	v_lshl_add_u32 v13, s13, 7, v12
	s_add_i32 s41, s0, 0x2000
	v_or_b32_e32 v2, v13, v10
	s_and_b32 s42, s97, 7
	v_add_u32_e32 v4, s41, v2
	v_mov_b64_e32 v[2:3], s[34:35]
	v_bfe_u32 v11, v1, 5, 1
	v_mad_i64_i32 v[4:5], s[0:1], v4, s9, v[2:3]
	s_lshl_b32 s2, s42, 7
	v_lshl_add_u64 v[152:153], v[4:5], 0, s[2:3]
	v_lshlrev_b32_e32 v4, 4, v11
	v_mov_b32_e32 v5, v0
	v_lshl_add_u64 v[6:7], v[152:153], 0, v[4:5]
	global_load_dwordx4 v[80:83], v[6:7], off
	global_load_dwordx4 v[84:87], v[6:7], off offset:32
	global_load_dwordx4 v[88:91], v[6:7], off offset:64
	global_load_dwordx4 v[92:95], v[6:7], off offset:96
	s_lshl_b32 s2, s13, 1
	v_sub_u32_e64 v5, s2, 2 clamp
	v_readlane_b32 s0, v246, 34
	s_min_u32 s2, s2, 60
	v_readfirstlane_b32 s13, v5
	s_or_b32 s0, s42, s0
	s_sub_i32 s59, s2, s13
	s_ashr_i32 s1, s0, 31
	s_add_i32 s56, s59, 3
	s_add_i32 s59, s59, 8
	s_cmp_lt_i32 s56, 0
	s_cselect_b64 s[50:51], -1, 0
	s_cmp_gt_i32 s56, -5
	v_ashrrev_i32_e32 v14, 2, v1
	s_cselect_b64 s[52:53], -1, 0
	s_not_b32 s2, s56
	v_lshl_add_u32 v6, s2, 6, v14
	s_lshl_b32 s2, s12, 1
	s_add_i32 s12, s2, s4
	v_lshlrev_b32_e32 v5, 6, v5
	s_ashr_i32 s13, s12, 31
	v_ashrrev_i32_e32 v7, 31, v6
	s_lshl_b32 s2, s40, 4
	v_or_b32_e32 v5, s41, v5
	s_lshl_b64 s[12:13], s[12:13], 15
	v_lshlrev_b64 v[6:7], 7, v[6:7]
	s_and_b32 s40, s2, 64
	v_add_u32_e32 v5, v5, v14
	v_and_b32_e32 v8, 63, v1
	v_lshl_add_u64 v[6:7], v[6:7], 0, s[12:13]
	v_mad_i64_i32 v[2:3], s[12:13], v5, s9, v[2:3]
	s_lshl_b32 s2, s40, 1
	v_cmp_gt_u32_e32 vcc, 32, v8
	v_lshlrev_b32_e32 v8, 4, v1
	s_add_u32 s12, s34, s2
	v_readlane_b32 s64, v246, 5
	v_and_b32_e32 v15, 48, v8
	s_addc_u32 s13, s35, 0
	s_lshl_b64 s[0:1], s[0:1], 2
	v_readlane_b32 s70, v246, 11
	v_mov_b32_e32 v8, v15
	v_mov_b32_e32 v9, v0
	v_readlane_b32 s71, v246, 12
	s_add_u32 s54, s70, s0
	v_lshl_add_u64 v[2:3], v[2:3], 0, s[2:3]
	v_lshl_add_u64 v[156:157], s[12:13], 0, v[8:9]
	s_addc_u32 s55, s71, s1
	s_add_i32 s12, s45, s97
	v_lshl_add_u64 v[154:155], v[2:3], 0, v[8:9]
	v_mul_lo_u32 v2, v14, s39
	s_bfe_u32 s0, s12, 0x50003
	v_add3_u32 v234, 0, v2, v8
	v_lshrrev_b32_e32 v249, 1, v15
	v_add3_u32 v249, 0, v2, v249
	v_add_u32_e32 v8, 0, v4
	v_lshlrev_b32_e32 v151, 2, v11
	v_lshrrev_b32_e32 v2, 2, v1
	v_and_b32_e32 v3, 16, v1
	v_lshlrev_b32_e32 v4, 3, v1
	s_lshl_b32 s2, s40, 2
	s_lshl_b32 s40, s0, 1
	v_and_or_b32 v2, v2, 3, v151
	v_lshlrev_b32_e32 v3, 1, v3
	v_and_b32_e32 v4, 24, v4
	s_min_u32 s41, s40, 2
	s_min_u32 s40, s40, 60
	v_add_u32_e32 v235, 0x9f, v13
	v_add_u32_e32 v236, 0xffffff80, v13
	v_add_u32_e32 v237, 0xffffff9f, v13
	v_add_u32_e32 v238, 0x41, v13
	v_add3_u32 v9, 0, v3, v4
	v_mul_u32_u24_e32 v13, 0x90, v2
	v_lshlrev_b64 v[2:3], 2, v[6:7]
	s_lshl_b32 s13, s0, 7
	v_and_b32_e32 v1, 3, v1
	s_add_i32 s40, s40, s41
	v_lshl_add_u64 v[4:5], s[84:85], 0, v[2:3]
	v_lshl_add_u64 v[2:3], s[86:87], 0, v[2:3]
	v_lshlrev_b32_e32 v162, 4, v1
	s_lshr_b32 s43, s12, 8
	v_add_u32_e32 v1, s13, v14
	s_lshl_b32 s40, s40, 6
	v_mov_b32_e32 v6, v15
	v_mov_b32_e32 v7, v0
	v_lshl_add_u64 v[2:3], v[2:3], 0, s[2:3]
	s_lshl_b32 s0, s43, 1
	v_subrev_u32_e32 v1, s40, v1
	v_lshl_add_u64 v[160:161], v[2:3], 0, v[6:7]
	s_add_i32 s0, s4, s0
	v_add_u32_e32 v2, 0xffffff40, v1
	s_ashr_i32 s1, s0, 31
	v_ashrrev_i32_e32 v3, 31, v2
	s_lshl_b64 s[0:1], s[0:1], 17
	v_lshlrev_b64 v[2:3], 9, v[2:3]
	v_lshl_add_u64 v[2:3], s[0:1], 0, v[2:3]
	s_lshl_b32 s0, s12, 6
	s_and_b32 s0, s0, 0x100
	v_or_b32_e32 v2, s0, v2
	s_lshl_b32 s0, s43, 12
	s_or_b32 s0, s13, s0
	s_lshl_b32 s42, s41, 6
	v_add_u32_e32 v1, s0, v14
	v_subrev_u32_e32 v1, s42, v1
	v_add_u32_e32 v239, 0x2040, v1
	v_sub_u32_e32 v1, v151, v10
	v_mul_u32_u24_e32 v11, 0x90, v10
	v_lshl_add_u64 v[4:5], v[4:5], 0, s[2:3]
	v_sub_u32_e32 v1, v1, v12
	v_cndmask_b32_e64 v233, 0, 1.0, vcc
	s_mov_b32 s60, 0
	v_lshl_add_u64 v[158:159], v[4:5], 0, v[6:7]
	s_sub_i32 s2, s13, s42
	v_mov_b32_e32 v163, v0
	v_lshl_add_u64 v[164:165], s[84:85], 0, v[2:3]
	v_lshl_add_u64 v[166:167], s[86:87], 0, v[2:3]
	v_subrev_u32_e32 v240, s42, v1
	v_add_u32_e32 v241, v8, v11
	v_add_u32_e32 v242, v9, v13
	v_readlane_b32 s65, v246, 6
	v_readlane_b32 s66, v246, 7
	v_readlane_b32 s67, v246, 8
	v_readlane_b32 s68, v246, 9
	v_readlane_b32 s69, v246, 10
	v_readlane_b32 s72, v246, 13
	v_readlane_b32 s73, v246, 14
	v_readlane_b32 s74, v246, 15
	v_readlane_b32 s75, v246, 16
	v_readlane_b32 s76, v246, 17
	v_readlane_b32 s77, v246, 18
	v_readlane_b32 s78, v246, 19
	v_readlane_b32 s79, v246, 20
	s_branch .LBB0_113

.LBB0_116:
	s_and_b64 vcc, exec, s[0:1]
	s_waitcnt vmcnt(1)
	v_mov_b64_e32 v[76:77], v[116:117]
	v_mov_b64_e32 v[78:79], v[118:119]
	v_mov_b64_e32 v[72:73], v[124:125]
	v_mov_b64_e32 v[74:75], v[126:127]
	v_mov_b64_e32 v[68:69], v[132:133]
	v_mov_b64_e32 v[70:71], v[134:135]
	v_mov_b64_e32 v[64:65], v[140:141]
	v_mov_b64_e32 v[66:67], v[142:143]
	v_mov_b64_e32 v[60:61], v[112:113]
	v_mov_b64_e32 v[62:63], v[114:115]
	v_mov_b64_e32 v[56:57], v[120:121]
	v_mov_b64_e32 v[58:59], v[122:123]
	v_mov_b64_e32 v[52:53], v[128:129]
	v_mov_b64_e32 v[54:55], v[130:131]
	v_mov_b64_e32 v[48:49], v[136:137]
	v_mov_b64_e32 v[50:51], v[138:139]
	s_cbranch_vccnz .LBB0_118
	global_load_dwordx4 v[48:51], v[158:159], off offset:192
	global_load_dwordx4 v[52:55], v[158:159], off offset:128
	global_load_dwordx4 v[56:59], v[158:159], off offset:64
	global_load_dwordx4 v[60:63], v[158:159], off
	global_load_dwordx4 v[64:67], v[160:161], off offset:192
	global_load_dwordx4 v[68:71], v[160:161], off offset:128
	global_load_dwordx4 v[72:75], v[160:161], off offset:64
	global_load_dwordx4 v[76:79], v[160:161], off

.LBB0_119:
	global_load_dwordx4 v[96:99], v[154:155], off offset:1024
	global_load_dwordx4 v[100:103], v[154:155], off offset:1088
	global_load_dwordx4 v[104:107], v[154:155], off offset:1280
	global_load_dwordx4 v[108:111], v[154:155], off offset:1344
	s_waitcnt vmcnt(11)
	v_mov_b64_e32 v[50:51], v[138:139]
	v_mov_b64_e32 v[48:49], v[136:137]
	s_waitcnt vmcnt(10)
	v_mov_b64_e32 v[54:55], v[130:131]
	v_mov_b64_e32 v[52:53], v[128:129]
	s_waitcnt vmcnt(9)
	v_mov_b64_e32 v[58:59], v[122:123]
	v_mov_b64_e32 v[56:57], v[120:121]
	s_waitcnt vmcnt(8)
	v_mov_b64_e32 v[62:63], v[114:115]
	v_mov_b64_e32 v[60:61], v[112:113]
	s_waitcnt vmcnt(7)
	v_mov_b64_e32 v[66:67], v[142:143]
	v_mov_b64_e32 v[64:65], v[140:141]
	s_waitcnt vmcnt(6)
	v_mov_b64_e32 v[70:71], v[134:135]
	v_mov_b64_e32 v[68:69], v[132:133]
	s_waitcnt vmcnt(5)
	v_mov_b64_e32 v[74:75], v[126:127]
	v_mov_b64_e32 v[72:73], v[124:125]
	s_waitcnt vmcnt(4)
	v_mov_b64_e32 v[78:79], v[118:119]
	v_mov_b64_e32 v[76:77], v[116:117]
	s_and_b64 vcc, exec, s[0:1]
	s_cbranch_vccnz .LBB0_111

.LBB0_121:
	s_add_i32 s40, s61, -1
	s_waitcnt lgkmcnt(0)
	s_barrier
	s_cmp_le_i32 s40, s56
	s_cselect_b64 s[0:1], -1, 0
	s_mov_b64 s[12:13], -1
	s_and_b64 vcc, exec, s[0:1]
	s_cbranch_vccz .LBB0_123
	ds_write_b128 v234, v[96:99]
	ds_write_b128 v234, v[100:103] offset:64
	ds_write_b128 v234, v[104:107] offset:9216
	ds_write_b128 v234, v[108:111] offset:9280
	s_mov_b64 s[12:13], 0
.LBB0_123:
	s_andn2_b64 vcc, exec, s[12:13]
	s_cbranch_vccnz .LBB0_125
	v_cvt_pk_bf16_f32 v5, v58, v59
	v_cvt_pk_bf16_f32 v4, v56, v57
	v_cvt_pk_bf16_f32 v3, v62, v63
	v_cvt_pk_bf16_f32 v2, v60, v61
	ds_write_b64 v249, v[2:3]
	ds_write_b64 v249, v[4:5] offset:32
	v_cvt_pk_bf16_f32 v5, v74, v75
	v_cvt_pk_bf16_f32 v4, v72, v73
	v_cvt_pk_bf16_f32 v3, v78, v79
	v_cvt_pk_bf16_f32 v2, v76, v77
	ds_write_b64 v249, v[2:3] offset:9216
	ds_write_b64 v249, v[4:5] offset:9248
	v_cvt_pk_bf16_f32 v5, v50, v51
	v_cvt_pk_bf16_f32 v4, v48, v49
	v_cvt_pk_bf16_f32 v3, v54, v55
	v_cvt_pk_bf16_f32 v2, v52, v53
	ds_write_b64 v249, v[2:3] offset:64
	ds_write_b64 v249, v[4:5] offset:96
	v_cvt_pk_bf16_f32 v5, v66, v67
	v_cvt_pk_bf16_f32 v4, v64, v65
	v_cvt_pk_bf16_f32 v3, v70, v71
	v_cvt_pk_bf16_f32 v2, v68, v69
	ds_write_b64 v249, v[2:3] offset:9280
	ds_write_b64 v249, v[4:5] offset:9312

.LBB0_129:
	s_cmp_ge_i32 s61, s59
	s_cbranch_scc1 .LBB0_131
	v_lshl_add_u64 v[2:3], v[170:171], 0, v[162:163]
	v_lshl_add_u64 v[4:5], v[168:169], 0, v[162:163]
	global_load_dwordx4 v[136:139], v[2:3], off offset:192
	global_load_dwordx4 v[128:131], v[2:3], off offset:128
	global_load_dwordx4 v[120:123], v[2:3], off offset:64
	global_load_dwordx4 v[112:115], v[2:3], off
	global_load_dwordx4 v[140:143], v[4:5], off offset:192
	global_load_dwordx4 v[132:135], v[4:5], off offset:128
	global_load_dwordx4 v[124:127], v[4:5], off offset:64
	global_load_dwordx4 v[116:119], v[4:5], off

.LBB0_132:
	v_add_u32_e32 v1, s44, v239
	v_mad_i64_i32 v[2:3], s[12:13], v1, s9, v[156:157]
	global_load_dwordx4 v[96:99], v[2:3], off offset:1024
	global_load_dwordx4 v[100:103], v[2:3], off offset:1088
	global_load_dwordx4 v[104:107], v[2:3], off offset:1280
	global_load_dwordx4 v[108:111], v[2:3], off offset:1344
	s_andn2_b64 vcc, exec, s[0:1]
	v_mov_b32_e32 v1, 0
	s_cbranch_vccnz .LBB0_128

.LBB0_134:
	v_cmp_ne_u32_e32 vcc, 1, v1
	ds_read_b128 v[2:5], v241
	ds_read_b128 v[6:9], v241 offset:4608
	ds_read_b128 v[10:13], v241 offset:32
	ds_read_b128 v[172:175], v241 offset:4640
	ds_read_b128 v[176:179], v241 offset:64
	ds_read_b128 v[180:183], v241 offset:4672
	ds_read_b128 v[184:187], v241 offset:96
	ds_read_b128 v[250:253], v241 offset:4704
	s_waitcnt lgkmcnt(7)
	v_mfma_f32_32x32x16_bf16 v[64:79], v[2:5], v[80:83], 0
	s_waitcnt lgkmcnt(6)
	v_mfma_f32_32x32x16_bf16 v[48:63], v[6:9], v[80:83], 0
	s_waitcnt lgkmcnt(5)
	v_mfma_f32_32x32x16_bf16 v[64:79], v[10:13], v[84:87], v[64:79]
	s_waitcnt lgkmcnt(4)
	v_mfma_f32_32x32x16_bf16 v[48:63], v[172:175], v[84:87], v[48:63]
	s_waitcnt lgkmcnt(3)
	v_mfma_f32_32x32x16_bf16 v[64:79], v[176:179], v[88:91], v[64:79]
	s_waitcnt lgkmcnt(2)
	v_mfma_f32_32x32x16_bf16 v[48:63], v[180:183], v[88:91], v[48:63]
	s_waitcnt lgkmcnt(1)
	v_mfma_f32_32x32x16_bf16 v[64:79], v[184:187], v[92:95], v[64:79]
	s_waitcnt lgkmcnt(0)
	v_mfma_f32_32x32x16_bf16 v[48:63], v[250:253], v[92:95], v[48:63]
	s_nop 7
	s_nop 3
	s_and_saveexec_b64 s[12:13], vcc
	s_xor_b64 s[40:41], exec, s[12:13]
	s_cbranch_execz .LBB0_136
	v_pk_mul_f32 v[172:173], v[64:65], s[38:39] op_sel_hi:[1,0]
	v_pk_mul_f32 v[14:15], v[66:67], s[38:39] op_sel_hi:[1,0]
	v_max3_f32 v1, v172, s20, v173
	v_max3_f32 v1, v1, v14, v15
	v_pk_mul_f32 v[10:11], v[68:69], s[38:39] op_sel_hi:[1,0]
	v_pk_mul_f32 v[12:13], v[70:71], s[38:39] op_sel_hi:[1,0]
	v_max3_f32 v1, v1, v10, v11
	v_max3_f32 v1, v1, v12, v13
	v_pk_mul_f32 v[2:3], v[72:73], s[38:39] op_sel_hi:[1,0]
	v_pk_mul_f32 v[4:5], v[74:75], s[38:39] op_sel_hi:[1,0]
	v_max3_f32 v1, v1, v2, v3
	v_max3_f32 v1, v1, v4, v5
	v_pk_mul_f32 v[6:7], v[76:77], s[38:39] op_sel_hi:[1,0]
	v_pk_mul_f32 v[8:9], v[78:79], s[38:39] op_sel_hi:[1,0]
	v_max3_f32 v1, v1, v6, v7
	v_max3_f32 v1, v1, v8, v9
	v_pk_mul_f32 v[174:175], v[48:49], s[38:39] op_sel_hi:[1,0]
	v_pk_mul_f32 v[176:177], v[50:51], s[38:39] op_sel_hi:[1,0]
	v_max3_f32 v1, v1, v174, v175
	v_max3_f32 v1, v1, v176, v177
	v_pk_mul_f32 v[178:179], v[52:53], s[38:39] op_sel_hi:[1,0]
	v_pk_mul_f32 v[180:181], v[54:55], s[38:39] op_sel_hi:[1,0]
	v_max3_f32 v1, v1, v178, v179
	v_max3_f32 v1, v1, v180, v181
	v_pk_mul_f32 v[182:183], v[56:57], s[38:39] op_sel_hi:[1,0]
	v_pk_mul_f32 v[184:185], v[58:59], s[38:39] op_sel_hi:[1,0]
	v_max3_f32 v1, v1, v182, v183
	v_max3_f32 v1, v1, v184, v185
	v_pk_mul_f32 v[186:187], v[60:61], s[38:39] op_sel_hi:[1,0]
	v_pk_mul_f32 v[188:189], v[62:63], s[38:39] op_sel_hi:[1,0]
	v_max3_f32 v1, v1, v186, v187
	v_max3_f32 v1, v1, v188, v189

.LBB0_141:
	s_or_b64 exec, exec, s[0:1]
	s_add_i32 s44, s44, 64
	s_add_i32 s0, s61, 1
	v_lshl_add_u64 v[170:171], v[170:171], 0, s[28:29]
	s_cmp_ge_i32 s61, s59
	v_lshl_add_u64 v[168:169], v[168:169], 0, s[28:29]
	s_cbranch_scc1 .LBB0_112
	s_mov_b32 s61, s0
	s_add_i32 s40, s61, -1
	s_cmp_le_i32 s40, s56
	s_cbranch_scc1 .Lattn_nocopy
	s_waitcnt vmcnt(7)
	v_mov_b64_e32 v[50:51], v[138:139]
	v_mov_b64_e32 v[48:49], v[136:137]
	s_waitcnt vmcnt(6)
	v_mov_b64_e32 v[54:55], v[130:131]
	v_mov_b64_e32 v[52:53], v[128:129]
	s_waitcnt vmcnt(5)
	v_mov_b64_e32 v[58:59], v[122:123]
	v_mov_b64_e32 v[56:57], v[120:121]
	s_waitcnt vmcnt(4)
	v_mov_b64_e32 v[62:63], v[114:115]
	v_mov_b64_e32 v[60:61], v[112:113]
	s_waitcnt vmcnt(3)
	v_mov_b64_e32 v[66:67], v[142:143]
	v_mov_b64_e32 v[64:65], v[140:141]
	s_waitcnt vmcnt(2)
	v_mov_b64_e32 v[70:71], v[134:135]
	v_mov_b64_e32 v[68:69], v[132:133]
	s_waitcnt vmcnt(1)
	v_mov_b64_e32 v[74:75], v[126:127]
	v_mov_b64_e32 v[72:73], v[124:125]
	s_waitcnt vmcnt(0)
	v_mov_b64_e32 v[78:79], v[118:119]
	v_mov_b64_e32 v[76:77], v[116:117]
	s_branch .LBB0_121
.Lattn_nocopy:
	s_waitcnt vmcnt(0)
	s_branch .LBB0_121

.LBB0_152:
	s_add_i32 s51, s50, 2
	s_min_u32 s0, s51, 63
	s_lshl_b32 s44, s0, 6
	s_xor_b32 s52, s44, 0xfc0
	s_and_b64 s[0:1], vcc, exec
	s_cselect_b32 s0, s44, s52
	s_or_b32 s0, s0, s13
	s_ashr_i32 s0, s0, 4
	s_or_b32 s0, s0, s2
	s_lshl_b32 s0, s0, 1
	s_or_b32 s0, s0, s12
	s_waitcnt lgkmcnt(0)
	s_barrier
	s_waitcnt vmcnt(19)
	ds_write_b128 v112, v[2:5]
	s_waitcnt vmcnt(1)
	ds_write_b128 v113, v[46:49]
	ds_write_b128 v114, v[6:9]
	ds_write_b128 v115, v[10:13]
	ds_write_b128 v116, v[14:17]
	ds_write_b128 v117, v[18:21]
	ds_write_b128 v118, v[22:25]
	ds_write_b128 v119, v[26:29]
	ds_write_b128 v120, v[34:37]
	ds_write_b128 v121, v[30:33]
	v_mad_i64_i32 v[30:31], s[0:1], s0, v225, v[106:107]
	v_add_co_u32_e64 v6, s[0:1], s17, v30
	v_lshlrev_b32_e32 v98, 2, v223
	s_nop 0
	v_addc_co_u32_e64 v7, s[0:1], 0, v31, s[0:1]
	v_add_co_u32_e64 v14, s[0:1], s18, v30
	s_waitcnt lgkmcnt(0)
	s_barrier
	ds_read_b128 v[164:167], v122
	ds_read_b128 v[168:171], v122 offset:64
	ds_read_b128 v[234:237], v122 offset:2368
	ds_read_b128 v[238:241], v122 offset:2304
	ds_read_b128 v[250:253], v122 offset:4608
	v_and_b32_e32 v98, 0x100, v98
	s_nop 0
	v_addc_co_u32_e64 v15, s[0:1], 0, v31, s[0:1]
	v_add_co_u32_e64 v22, s[0:1], s19, v30
	global_load_dwordx4 v[2:5], v[30:31], off
	s_nop 0
	v_addc_co_u32_e64 v23, s[0:1], 0, v31, s[0:1]
	v_add_co_u32_e64 v32, s[0:1], s14, v30
	global_load_dwordx4 v[46:49], v[6:7], off offset:-4096
	s_nop 0
	global_load_dwordx4 v[6:9], v[6:7], off
	v_addc_co_u32_e64 v33, s[0:1], 0, v31, s[0:1]
	global_load_dwordx4 v[10:13], v[14:15], off offset:-4096
	s_nop 0
	global_load_dwordx4 v[14:17], v[14:15], off
	s_nop 0
	global_load_dwordx4 v[18:21], v[22:23], off offset:-4096
	s_nop 0
	global_load_dwordx4 v[22:25], v[22:23], off
	s_nop 0
	global_load_dwordx4 v[26:29], v[32:33], off offset:-4096
	global_load_dwordx4 v[34:37], v[32:33], off
	v_add_u32_e32 v110, s42, v98
	s_nop 0
	s_nop 0
	v_cvt_pk_bf16_f32 v105, v92, v93
	v_cvt_pk_bf16_f32 v104, v90, v91
	v_cvt_pk_bf16_f32 v103, v96, v97
	v_cvt_pk_bf16_f32 v102, v94, v95
	v_cvt_pk_bf16_f32 v133, v84, v85
	v_cvt_pk_bf16_f32 v132, v82, v83
	s_nop 0
	s_waitcnt lgkmcnt(4)
	v_mfma_f32_16x16x32_bf16 v[98:101], v[164:167], v[102:105], 0
	ds_read_b128 v[164:167], v122 offset:4672
	v_cvt_pk_bf16_f32 v131, v88, v89
	v_cvt_pk_bf16_f32 v130, v86, v87
	s_nop 0
	v_add_co_u32_e64 v30, s[0:1], s15, v30
	s_nop 0
	s_waitcnt lgkmcnt(4)
	v_mfma_f32_16x16x32_bf16 v[98:101], v[168:171], v[130:133], v[98:101]
	ds_read_b128 v[168:171], v122 offset:6912
	s_nop 0
	v_addc_co_u32_e64 v31, s[0:1], 0, v31, s[0:1]
	s_nop 0
	s_waitcnt lgkmcnt(3)
	v_mfma_f32_16x16x32_bf16 v[126:129], v[238:241], v[102:105], 0
	ds_read_b128 v[238:241], v122 offset:6976
	global_load_dwordx4 v[30:33], v[30:31], off
	s_add_i32 s44, s43, 1
	s_and_b64 s[0:1], vcc, exec
	v_mfma_f32_16x16x32_bf16 v[126:129], v[234:237], v[130:133], v[126:129]
	ds_read_b128 v[234:237], v124 offset:9280
	ds_read2_b64 v[134:137], v123 offset1:4
	s_nop 0
	s_nop 0
	s_cselect_b32 s0, s50, s44
	s_nop 0
	s_waitcnt lgkmcnt(5)
	v_mfma_f32_16x16x32_bf16 v[138:141], v[250:253], v[102:105], 0
	ds_read_b128 v[250:253], v124 offset:9216
	s_waitcnt lgkmcnt(1)
	v_and_b32_e32 v143, 0xffff0000, v134
	v_lshlrev_b32_e32 v142, 16, v134
	v_pk_add_f32 v[98:99], v[142:143], v[98:99] neg_lo:[0,1] neg_hi:[0,1]
	s_nop 0
	v_mfma_f32_16x16x32_bf16 v[138:141], v[164:167], v[130:133], v[138:141]
	ds_read_b128 v[164:167], v124 offset:18432
	ds_read2_b64 v[152:155], v123 offset0:8 offset1:12
	s_nop 0
	s_nop 0
	v_and_b32_e32 v143, 0xffff0000, v135
	v_lshlrev_b32_e32 v142, 16, v135
	v_pk_add_f32 v[100:101], v[142:143], v[100:101] neg_lo:[0,1] neg_hi:[0,1]
	s_nop 0
	v_mfma_f32_16x16x32_bf16 v[156:159], v[168:171], v[102:105], 0
	ds_read_b128 v[168:171], v124 offset:18496
	v_cvt_pk_bf16_f32 v98, v98, v99
	v_cvt_pk_bf16_f32 v99, v100, v101
	v_and_b32_e32 v101, 0xffff0000, v136
	v_lshlrev_b32_e32 v100, 16, v136
	v_pk_add_f32 v[100:101], v[100:101], v[126:127] neg_lo:[0,1] neg_hi:[0,1]
	v_and_b32_e32 v127, 0xffff0000, v137
	v_lshlrev_b32_e32 v126, 16, v137
	v_pk_add_f32 v[126:127], v[126:127], v[128:129] neg_lo:[0,1] neg_hi:[0,1]
	v_cvt_pk_bf16_f32 v100, v100, v101
	v_cvt_pk_bf16_f32 v101, v126, v127
	s_waitcnt lgkmcnt(1)
	v_and_b32_e32 v127, 0xffff0000, v152
	v_lshlrev_b32_e32 v126, 16, v152
	v_and_b32_e32 v129, 0xffff0000, v153
	v_lshlrev_b32_e32 v128, 16, v153
	v_pk_add_f32 v[126:127], v[126:127], v[138:139] neg_lo:[0,1] neg_hi:[0,1]
	v_pk_add_f32 v[128:129], v[128:129], v[140:141] neg_lo:[0,1] neg_hi:[0,1]
	s_nop 0
	s_nop 0
	v_mfma_f32_16x16x32_bf16 v[156:159], v[238:241], v[130:133], v[156:159]
	ds_read_b128 v[238:241], v124 offset:11584
	v_cvt_pk_bf16_f32 v126, v126, v127
	v_cvt_pk_bf16_f32 v127, v128, v129
	v_and_b32_e32 v129, 0xffff0000, v154
	v_lshlrev_b32_e32 v128, 16, v154
	v_and_b32_e32 v135, 0xffff0000, v155
	v_lshlrev_b32_e32 v134, 16, v155
	s_nop 1
	v_pk_add_f32 v[128:129], v[128:129], v[156:157] neg_lo:[0,1] neg_hi:[0,1]
	v_pk_add_f32 v[134:135], v[134:135], v[158:159] neg_lo:[0,1] neg_hi:[0,1]
	v_cvt_pk_bf16_f32 v128, v128, v129
	v_cvt_pk_bf16_f32 v129, v134, v135
	s_nop 0
	s_nop 0
	v_mfma_f32_16x16x32_bf16 v[134:137], v[102:105], v[250:253], 0
	ds_read_b128 v[250:253], v124 offset:11520
	v_lshl_add_u32 v125, s0, 6, v111
	v_mad_i64_i32 v[142:143], s[0:1], v125, s9, v[108:109]
	v_mfma_f32_16x16x32_bf16 v[134:137], v[130:133], v[234:237], v[134:137]
	ds_read_b128 v[234:237], v124 offset:20736
	s_nop 0
	s_min_u32 s0, s50, 60
	s_add_i32 s44, s0, 3
	s_nop 0
	v_mfma_f32_16x16x32_bf16 v[134:137], v[98:101], v[164:167], v[134:137]
	ds_read_b128 v[164:167], v124 offset:20800
	s_nop 0
	s_sub_i32 s52, 60, s0
	s_and_b64 s[0:1], vcc, exec
	s_nop 0
	s_waitcnt lgkmcnt(4)
	v_mfma_f32_16x16x32_bf16 v[134:137], v[126:129], v[168:171], v[134:137]
	ds_read_b128 v[168:171], v124 offset:13888
	s_nop 0
	s_cselect_b32 s0, s44, s52
	s_lshl_b32 s0, s0, 6
	s_nop 4
	v_cvt_pk_bf16_f32 v137, v136, v137
	v_cvt_pk_bf16_f32 v136, v134, v135
	global_store_dwordx2 v[142:143], v[136:137], off
	s_nop 0
	s_nop 0
	s_waitcnt lgkmcnt(3)
	v_mfma_f32_16x16x32_bf16 v[134:137], v[102:105], v[250:253], 0
	ds_read_b128 v[250:253], v124 offset:13824
	v_lshl_add_u64 v[142:143], v[142:143], 0, s[40:41]
	s_add_i32 s0, s0, s13
	s_ashr_i32 s0, s0, 4
	v_mfma_f32_16x16x32_bf16 v[134:137], v[130:133], v[238:241], v[134:137]
	ds_read_b128 v[238:241], v124 offset:23040
	s_nop 0
	s_or_b32 s0, s0, s2
	s_lshl_b32 s0, s0, 1
	s_nop 0
	s_waitcnt lgkmcnt(4)
	v_mfma_f32_16x16x32_bf16 v[134:137], v[98:101], v[234:237], v[134:137]
	ds_read_b128 v[234:237], v124 offset:23104
	s_nop 0
	s_or_b32 s0, s0, s12
	s_add_i32 s44, s50, 1
	s_nop 0
	s_waitcnt lgkmcnt(4)
	v_mfma_f32_16x16x32_bf16 v[134:137], v[126:129], v[164:167], v[134:137]
	ds_read_b128 v[164:167], v124 offset:16128
	s_nop 0
	s_nop 6
	v_cvt_pk_bf16_f32 v137, v136, v137
	v_cvt_pk_bf16_f32 v136, v134, v135
	global_store_dwordx2 v[142:143], v[136:137], off
	s_nop 0
	s_nop 0
	s_waitcnt lgkmcnt(3)
	v_mfma_f32_16x16x32_bf16 v[134:137], v[102:105], v[250:253], 0
	ds_read_b128 v[250:253], v124 offset:16192
	v_mfma_f32_16x16x32_bf16 v[134:137], v[130:133], v[168:171], v[134:137]
	ds_read_b128 v[168:171], v124 offset:25344
	s_nop 0
	s_nop 0
	s_waitcnt lgkmcnt(4)
	v_mfma_f32_16x16x32_bf16 v[134:137], v[98:101], v[238:241], v[134:137]
	ds_read_b128 v[238:241], v124 offset:25408
	s_nop 0
	s_nop 0
	s_waitcnt lgkmcnt(4)
	v_mfma_f32_16x16x32_bf16 v[134:137], v[126:129], v[234:237], v[134:137]
	ds_read_b128 v[234:237], v124 offset:27648
	v_lshl_add_u64 v[138:139], v[142:143], 0, s[40:41]
	s_nop 6
	v_cvt_pk_bf16_f32 v137, v136, v137
	v_cvt_pk_bf16_f32 v136, v134, v135
	global_store_dwordx2 v[138:139], v[136:137], off
	s_nop 0
	s_nop 0
	s_waitcnt lgkmcnt(4)
	v_mfma_f32_16x16x32_bf16 v[102:105], v[102:105], v[164:167], 0
	ds_read_b128 v[164:167], v124 offset:27712
	s_nop 0
	s_nop 0
	s_waitcnt lgkmcnt(4)
	v_mfma_f32_16x16x32_bf16 v[102:105], v[130:133], v[250:253], v[102:105]
	ds_read_b128 v[250:253], v124 offset:29952
	s_nop 0
	s_nop 0
	s_waitcnt lgkmcnt(4)
	v_mfma_f32_16x16x32_bf16 v[102:105], v[98:101], v[168:171], v[102:105]
	ds_read_b128 v[168:171], v124 offset:30016
	s_nop 0
	s_nop 0
	s_waitcnt lgkmcnt(4)
	v_mfma_f32_16x16x32_bf16 v[102:105], v[126:129], v[238:241], v[102:105]
	ds_read_b128 v[238:241], v124 offset:32256
	ds_bpermute_b32 v130, v110, v1
	ds_bpermute_b32 v110, v110, v1 offset:4
	s_nop 0
	s_waitcnt lgkmcnt(1)
	v_pk_mul_f32 v[96:97], v[96:97], v[130:131] op_sel_hi:[1,0]
	s_nop 3
	v_cvt_pk_bf16_f32 v105, v104, v105
	v_cvt_pk_bf16_f32 v104, v102, v103
	v_lshl_add_u64 v[102:103], v[138:139], 0, s[40:41]
	global_store_dwordx2 v[102:103], v[104:105], off
	s_nop 0
	v_pk_mul_f32 v[94:95], v[94:95], v[130:131] op_sel_hi:[1,0]
	v_pk_mul_f32 v[92:93], v[92:93], v[130:131] op_sel_hi:[1,0]
	v_pk_mul_f32 v[90:91], v[90:91], v[130:131] op_sel_hi:[1,0]
	s_nop 0
	v_mfma_f32_16x16x32_bf16 v[94:97], v[234:237], v[98:101], v[94:97]
	ds_read_b128 v[234:237], v124 offset:32320
	s_nop 0
	v_pk_mul_f32 v[88:89], v[88:89], v[130:131] op_sel_hi:[1,0]
	v_pk_mul_f32 v[86:87], v[86:87], v[130:131] op_sel_hi:[1,0]
	s_nop 0
	v_mfma_f32_16x16x32_bf16 v[94:97], v[164:167], v[126:129], v[94:97]
	ds_read_b128 v[164:167], v124 offset:34560
	s_nop 0
	v_pk_mul_f32 v[84:85], v[84:85], v[130:131] op_sel_hi:[1,0]
	v_pk_mul_f32 v[82:83], v[82:83], v[130:131] op_sel_hi:[1,0]
	s_nop 0
	v_mfma_f32_16x16x32_bf16 v[90:93], v[250:253], v[98:101], v[90:93]
	s_nop 0
	s_nop 0
	v_mfma_f32_16x16x32_bf16 v[90:93], v[168:171], v[126:129], v[90:93]
	s_nop 0
	s_nop 0
	v_mfma_f32_16x16x32_bf16 v[86:89], v[238:241], v[98:101], v[86:89]
	s_nop 0
	s_nop 0
	s_waitcnt lgkmcnt(1)
	v_mfma_f32_16x16x32_bf16 v[86:89], v[234:237], v[126:129], v[86:89]
	s_nop 0
	s_nop 6
	v_cvt_pk_bf16_f32 v131, v88, v89
	s_nop 0
	s_waitcnt lgkmcnt(0)
	v_mfma_f32_16x16x32_bf16 v[82:85], v[164:167], v[98:101], v[82:85]
	ds_read_b128 v[98:101], v124 offset:34624
	s_waitcnt lgkmcnt(0)
	s_barrier
	ds_write_b128 v112, v[58:61]
	ds_write_b128 v113, v[78:81]
	ds_write_b128 v114, v[74:77]
	ds_write_b128 v115, v[70:73]
	ds_write_b128 v116, v[66:69]
	ds_write_b128 v117, v[62:65]
	ds_write_b128 v118, v[54:57]
	ds_write_b128 v119, v[50:53]
	ds_write_b128 v120, v[38:41]
	s_waitcnt vmcnt(14)
	ds_write_b128 v121, v[42:45]
	v_mad_i64_i32 v[58:59], s[0:1], s0, v225, v[106:107]
	v_add_co_u32_e64 v38, s[0:1], s15, v58
	s_waitcnt lgkmcnt(0)
	s_barrier
	ds_read_b128 v[164:167], v122
	ds_read_b128 v[168:171], v122 offset:64
	ds_read_b128 v[234:237], v122 offset:2368
	ds_read_b128 v[238:241], v122 offset:2304
	ds_read_b128 v[250:253], v122 offset:4608
	s_nop 0
	v_mfma_f32_16x16x32_bf16 v[82:85], v[98:101], v[126:129], v[82:85]
	v_addc_co_u32_e64 v39, s[0:1], 0, v59, s[0:1]
	global_load_dwordx4 v[42:45], v[38:39], off
	v_add_co_u32_e64 v38, s[0:1], s14, v58
	v_cvt_pk_bf16_f32 v129, v92, v93
	s_nop 0
	v_addc_co_u32_e64 v39, s[0:1], 0, v59, s[0:1]
	s_movk_i32 s0, 0x7000
	s_nop 0
	v_add_co_u32_e64 v50, s[0:1], s0, v58
	global_load_dwordx4 v[38:41], v[38:39], off
	s_nop 0
	v_addc_co_u32_e64 v51, s[0:1], 0, v59, s[0:1]
	v_add_co_u32_e64 v54, s[0:1], s19, v58
	global_load_dwordx4 v[50:53], v[50:51], off
	s_nop 0
	v_addc_co_u32_e64 v55, s[0:1], 0, v59, s[0:1]
	s_movk_i32 s0, 0x5000
	s_nop 0
	v_add_co_u32_e64 v60, s[0:1], s0, v58
	global_load_dwordx4 v[54:57], v[54:55], off
	s_nop 0
	v_addc_co_u32_e64 v61, s[0:1], 0, v59, s[0:1]
	global_load_dwordx4 v[62:65], v[60:61], off
	v_add_co_u32_e64 v60, s[0:1], s18, v58
	v_cvt_pk_bf16_f32 v128, v90, v91
	s_nop 0
	v_addc_co_u32_e64 v61, s[0:1], 0, v59, s[0:1]
	global_load_dwordx4 v[66:69], v[60:61], off
	v_add_co_u32_e64 v60, s[0:1], s16, v58
	v_cvt_pk_bf16_f32 v127, v96, v97
	s_nop 0
	v_addc_co_u32_e64 v61, s[0:1], 0, v59, s[0:1]
	global_load_dwordx4 v[70:73], v[60:61], off
	v_add_co_u32_e64 v60, s[0:1], s17, v58
	v_cvt_pk_bf16_f32 v126, v94, v95
	s_nop 0
	v_addc_co_u32_e64 v61, s[0:1], 0, v59, s[0:1]
	global_load_dwordx4 v[74:77], v[60:61], off
	v_add_co_u32_e64 v60, s[0:1], s7, v58
	v_cvt_pk_bf16_f32 v133, v84, v85
	s_nop 0
	v_addc_co_u32_e64 v61, s[0:1], 0, v59, s[0:1]
	global_load_dwordx4 v[78:81], v[60:61], off
	s_nop 0
	global_load_dwordx4 v[58:61], v[58:59], off
	s_nop 0
	s_nop 0
	s_nop 0
	s_waitcnt lgkmcnt(4)
	v_mfma_f32_16x16x32_bf16 v[98:101], v[164:167], v[126:129], 0
	ds_read_b128 v[164:167], v122 offset:4672
	v_cvt_pk_bf16_f32 v132, v82, v83
	v_cvt_pk_bf16_f32 v130, v86, v87
	s_nop 0
	s_and_b64 s[0:1], vcc, exec
	s_nop 0
	s_waitcnt lgkmcnt(4)
	v_mfma_f32_16x16x32_bf16 v[98:101], v[168:171], v[130:133], v[98:101]
	ds_read_b128 v[168:171], v122 offset:6912
	s_nop 0
	s_cselect_b32 s0, s44, s43
	v_lshl_add_u32 v125, s0, 6, v111
	s_nop 0
	s_waitcnt lgkmcnt(3)
	v_mfma_f32_16x16x32_bf16 v[102:105], v[238:241], v[126:129], 0
	ds_read_b128 v[238:241], v122 offset:6976
	v_mul_f32_e64 v96, v96, v110
	v_mul_f32_e64 v97, v97, v110
	v_pk_mul_f32 v[94:95], v[94:95], v[110:111] op_sel_hi:[1,0]
	v_pk_mul_f32 v[92:93], v[92:93], v[110:111] op_sel_hi:[1,0]
	v_mfma_f32_16x16x32_bf16 v[134:137], v[234:237], v[130:133], v[102:105]
	ds_read_b128 v[234:237], v124 offset:9280
	s_nop 2
	ds_read2_b64 v[102:105], v123 offset1:4
	s_nop 0
	s_nop 0
	v_pk_mul_f32 v[90:91], v[90:91], v[110:111] op_sel_hi:[1,0]
	s_nop 0
	s_waitcnt lgkmcnt(5)
	v_mfma_f32_16x16x32_bf16 v[138:141], v[250:253], v[126:129], 0
	ds_read_b128 v[250:253], v124 offset:9216
	s_waitcnt lgkmcnt(1)
	v_and_b32_e32 v143, 0xffff0000, v102
	v_lshlrev_b32_e32 v142, 16, v102
	v_pk_add_f32 v[98:99], v[142:143], v[98:99] neg_lo:[0,1] neg_hi:[0,1]
	s_nop 0
	v_mfma_f32_16x16x32_bf16 v[138:141], v[164:167], v[130:133], v[138:141]
	ds_read_b128 v[164:167], v124 offset:18432
	ds_read2_b64 v[152:155], v123 offset0:8 offset1:12
	s_nop 0
	s_nop 0
	v_cvt_pk_bf16_f32 v102, v98, v99
	v_and_b32_e32 v99, 0xffff0000, v103
	v_lshlrev_b32_e32 v98, 16, v103
	v_pk_add_f32 v[98:99], v[98:99], v[100:101] neg_lo:[0,1] neg_hi:[0,1]
	s_nop 0
	v_mfma_f32_16x16x32_bf16 v[156:159], v[168:171], v[126:129], 0
	ds_read_b128 v[168:171], v124 offset:18496
	v_cvt_pk_bf16_f32 v103, v98, v99
	v_and_b32_e32 v99, 0xffff0000, v104
	v_lshlrev_b32_e32 v98, 16, v104
	v_pk_add_f32 v[98:99], v[98:99], v[134:135] neg_lo:[0,1] neg_hi:[0,1]
	s_waitcnt lgkmcnt(1)
	v_and_b32_e32 v101, 0xffff0000, v153
	v_cvt_pk_bf16_f32 v104, v98, v99
	v_and_b32_e32 v99, 0xffff0000, v105
	v_lshlrev_b32_e32 v98, 16, v105
	v_pk_add_f32 v[98:99], v[98:99], v[136:137] neg_lo:[0,1] neg_hi:[0,1]
	v_lshlrev_b32_e32 v100, 16, v153
	v_cvt_pk_bf16_f32 v105, v98, v99
	v_and_b32_e32 v99, 0xffff0000, v152
	v_lshlrev_b32_e32 v98, 16, v152
	v_pk_add_f32 v[98:99], v[98:99], v[138:139] neg_lo:[0,1] neg_hi:[0,1]
	v_pk_add_f32 v[100:101], v[100:101], v[140:141] neg_lo:[0,1] neg_hi:[0,1]
	s_nop 0
	s_nop 0
	v_mfma_f32_16x16x32_bf16 v[156:159], v[238:241], v[130:133], v[156:159]
	ds_read_b128 v[238:241], v124 offset:11584
	v_cvt_pk_bf16_f32 v98, v98, v99
	v_cvt_pk_bf16_f32 v99, v100, v101
	v_and_b32_e32 v101, 0xffff0000, v154
	v_lshlrev_b32_e32 v100, 16, v154
	v_and_b32_e32 v135, 0xffff0000, v155
	v_lshlrev_b32_e32 v134, 16, v155
	s_nop 1
	v_pk_add_f32 v[100:101], v[100:101], v[156:157] neg_lo:[0,1] neg_hi:[0,1]
	v_pk_add_f32 v[134:135], v[134:135], v[158:159] neg_lo:[0,1] neg_hi:[0,1]
	v_cvt_pk_bf16_f32 v100, v100, v101
	v_cvt_pk_bf16_f32 v101, v134, v135
	s_nop 0
	s_nop 0
	v_mfma_f32_16x16x32_bf16 v[134:137], v[126:129], v[250:253], 0
	ds_read_b128 v[250:253], v124 offset:11520
	v_mad_i64_i32 v[142:143], s[0:1], v125, s9, v[108:109]
	v_pk_mul_f32 v[88:89], v[88:89], v[110:111] op_sel_hi:[1,0]
	v_mfma_f32_16x16x32_bf16 v[134:137], v[130:133], v[234:237], v[134:137]
	ds_read_b128 v[234:237], v124 offset:20736
	s_nop 0
	v_pk_mul_f32 v[86:87], v[86:87], v[110:111] op_sel_hi:[1,0]
	v_pk_mul_f32 v[84:85], v[84:85], v[110:111] op_sel_hi:[1,0]
	s_nop 0
	v_mfma_f32_16x16x32_bf16 v[134:137], v[102:105], v[164:167], v[134:137]
	ds_read_b128 v[164:167], v124 offset:20800
	s_nop 0
	v_pk_mul_f32 v[82:83], v[82:83], v[110:111] op_sel_hi:[1,0]
	s_add_i32 s42, s42, 8
	s_nop 0
	s_waitcnt lgkmcnt(4)
	v_mfma_f32_16x16x32_bf16 v[134:137], v[98:101], v[168:171], v[134:137]
	ds_read_b128 v[168:171], v124 offset:13888
	s_nop 0
	s_add_i32 s43, s43, -2
	s_cmp_lt_u32 s50, 62
	s_nop 4
	v_cvt_pk_bf16_f32 v137, v136, v137
	v_cvt_pk_bf16_f32 v136, v134, v135
	global_store_dwordx2 v[142:143], v[136:137], off
	s_nop 0
	s_nop 0
	s_waitcnt lgkmcnt(3)
	v_mfma_f32_16x16x32_bf16 v[134:137], v[126:129], v[250:253], 0
	ds_read_b128 v[250:253], v124 offset:13824
	v_lshl_add_u64 v[142:143], v[142:143], 0, s[40:41]
	s_mov_b32 s50, s51
	v_mfma_f32_16x16x32_bf16 v[134:137], v[130:133], v[238:241], v[134:137]
	ds_read_b128 v[238:241], v124 offset:23040
	s_nop 0
	s_nop 0
	s_waitcnt lgkmcnt(4)
	v_mfma_f32_16x16x32_bf16 v[134:137], v[102:105], v[234:237], v[134:137]
	ds_read_b128 v[234:237], v124 offset:23104
	s_nop 0
	s_nop 0
	s_waitcnt lgkmcnt(4)
	v_mfma_f32_16x16x32_bf16 v[134:137], v[98:101], v[164:167], v[134:137]
	ds_read_b128 v[164:167], v124 offset:16128
	s_nop 0
	s_nop 6
	v_cvt_pk_bf16_f32 v137, v136, v137
	v_cvt_pk_bf16_f32 v136, v134, v135
	global_store_dwordx2 v[142:143], v[136:137], off
	s_nop 0
	s_nop 0
	s_waitcnt lgkmcnt(3)
	v_mfma_f32_16x16x32_bf16 v[134:137], v[126:129], v[250:253], 0
	ds_read_b128 v[250:253], v124 offset:16192
	v_mfma_f32_16x16x32_bf16 v[134:137], v[130:133], v[168:171], v[134:137]
	ds_read_b128 v[168:171], v124 offset:25344
	s_nop 0
	s_nop 0
	s_waitcnt lgkmcnt(4)
	v_mfma_f32_16x16x32_bf16 v[134:137], v[102:105], v[238:241], v[134:137]
	ds_read_b128 v[238:241], v124 offset:25408
	s_nop 0
	s_nop 0
	s_waitcnt lgkmcnt(4)
	v_mfma_f32_16x16x32_bf16 v[134:137], v[98:101], v[234:237], v[134:137]
	ds_read_b128 v[234:237], v124 offset:27648
	v_lshl_add_u64 v[138:139], v[142:143], 0, s[40:41]
	s_nop 6
	v_cvt_pk_bf16_f32 v137, v136, v137
	v_cvt_pk_bf16_f32 v136, v134, v135
	global_store_dwordx2 v[138:139], v[136:137], off
	s_nop 0
	s_nop 0
	s_waitcnt lgkmcnt(4)
	v_mfma_f32_16x16x32_bf16 v[126:129], v[126:129], v[164:167], 0
	ds_read_b128 v[164:167], v124 offset:27712
	s_nop 0
	s_nop 0
	s_waitcnt lgkmcnt(4)
	v_mfma_f32_16x16x32_bf16 v[126:129], v[130:133], v[250:253], v[126:129]
	ds_read_b128 v[250:253], v124 offset:29952
	s_nop 0
	s_nop 0
	s_waitcnt lgkmcnt(4)
	v_mfma_f32_16x16x32_bf16 v[126:129], v[102:105], v[168:171], v[126:129]
	ds_read_b128 v[168:171], v124 offset:30016
	s_nop 0
	s_nop 0
	s_waitcnt lgkmcnt(4)
	v_mfma_f32_16x16x32_bf16 v[126:129], v[98:101], v[238:241], v[126:129]
	ds_read_b128 v[238:241], v124 offset:32256
	s_nop 7
	v_cvt_pk_bf16_f32 v129, v128, v129
	v_cvt_pk_bf16_f32 v128, v126, v127
	v_lshl_add_u64 v[126:127], v[138:139], 0, s[40:41]
	global_store_dwordx2 v[126:127], v[128:129], off
	s_nop 0
	s_nop 0
	s_waitcnt lgkmcnt(4)
	v_mfma_f32_16x16x32_bf16 v[94:97], v[234:237], v[102:105], v[94:97]
	ds_read_b128 v[234:237], v124 offset:32320
	s_nop 0
	s_nop 0
	s_waitcnt lgkmcnt(4)
	v_mfma_f32_16x16x32_bf16 v[94:97], v[164:167], v[98:101], v[94:97]
	ds_read_b128 v[164:167], v124 offset:34560
	s_nop 0
	s_nop 0
	s_waitcnt lgkmcnt(4)
	v_mfma_f32_16x16x32_bf16 v[90:93], v[250:253], v[102:105], v[90:93]
	ds_read_b128 v[250:253], v124 offset:34624
	s_nop 0
	s_nop 0
	s_waitcnt lgkmcnt(4)
	v_mfma_f32_16x16x32_bf16 v[90:93], v[168:171], v[98:101], v[90:93]
	s_nop 0
	s_nop 0
	s_waitcnt lgkmcnt(3)
	v_mfma_f32_16x16x32_bf16 v[86:89], v[238:241], v[102:105], v[86:89]
	s_nop 0
	s_nop 0
	s_waitcnt lgkmcnt(2)
	v_mfma_f32_16x16x32_bf16 v[86:89], v[234:237], v[98:101], v[86:89]
	s_nop 0
	s_nop 0
	s_waitcnt lgkmcnt(1)
	v_mfma_f32_16x16x32_bf16 v[82:85], v[164:167], v[102:105], v[82:85]
	s_nop 0
	s_nop 0
	s_waitcnt lgkmcnt(0)
	v_mfma_f32_16x16x32_bf16 v[82:85], v[250:253], v[98:101], v[82:85]
	s_cbranch_scc1 .LBB0_152
	s_setprio 0
	s_branch .LBB0_85
